# V phase: exact counted ring waits in the block that also loads the output tile (four more loads may stay outstanding)
# baseline (speedup 1.0000x reference)
; #define FP8_LO(w) __builtin_amdgcn_cvt_pk_f32_fp8((int)(w), false)
; #define FP8_HI(w) __builtin_amdgcn_cvt_pk_f32_fp8((int)(w), true)
; DI void axpy16h(float (&acc)[16], float g, const u32x4 w) {
;     const f32x2 a0 = FP8_LO(w.x), a1 = FP8_HI(w.x), a2 = FP8_LO(w.y), a3 = FP8_HI(w.y), a4 = FP8_LO(w.z), a5 = FP8_HI(w.z), a6 = FP8_LO(w.w), a7 = FP8_HI(w.w);
;     acc[0] += g * a0.x; acc[1] += g * a0.y; acc[2] += g * a1.x; acc[3] += g * a1.y; acc[4] += g * a2.x; acc[5] += g * a2.y; acc[6] += g * a3.x; acc[7] += g * a3.y;
;     acc[8] += g * a4.x; acc[9] += g * a4.y; acc[10] += g * a5.x; acc[11] += g * a5.y; acc[12] += g * a6.x; acc[13] += g * a6.y; acc[14] += g * a7.x; acc[15] += g * a7.y;
; DI void phase_peer_v(const Args& a, int layer, int ci) {
;     ...
;             for (int g8 = 0; g8 < 16; ++g8) {
;                 u32x4 nxt[8];
;                 if (g8 < 15) gat_loadh(V, idA, idB, g8 + 1, lo16, nxt); else gat_loadh(V, idAn, idBn, 0, lo16, nxt);
;                 const float ghs = g8 < 8 ? ghA : ghB;
; #pragma unroll
;                 for (int j = 0; j < 8; ++j) { const float gv = __shfl(ghs, (g8 & 7) * 8 + j); axpy16h(acc, gv, cur[j]); if (j & 1) __builtin_amdgcn_sched_barrier(0); }
; #pragma unroll
;                 for (int j = 0; j < 8; ++j) cur[j] = nxt[j];
;             }
.Lpv_b1_noout:
	s_waitcnt lgkmcnt(0)
	s_bfe_u32 s45, s44, 0x10003
	s_lshl_b32 s45, s45, 12
	s_and_b32 s46, s44, 7
	s_lshl_b32 s46, s46, 6
	s_add_u32 s45, s45, s46
	s_add_u32 s45, s45, 0x2000
	v_add_u32_e32 v5, s45, v240
	ds_read_b128 v[104:107], v5
	ds_read_b128 v[108:111], v5 offset:16
	ds_read_b128 v[112:115], v5 offset:32
	ds_read_b128 v[116:119], v5 offset:48
	s_add_u32 s44, s0, 2
	s_min_u32 s44, s44, 0xff
	s_bfe_u32 s45, s44, 0x10003
	s_lshl_b32 s45, s45, 12
	s_and_b32 s46, s44, 7
	s_lshl_b32 s46, s46, 6
	s_add_u32 s45, s45, s46
	v_add_u32_e32 v5, s45, v240
	ds_read_b128 v[88:91], v5
	ds_read_b128 v[92:95], v5 offset:16
	ds_read_b128 v[96:99], v5 offset:32
	ds_read_b128 v[100:103], v5 offset:48
	s_cmp_eq_u32 s47, 7
	s_cbranch_scc1 .Lpv_b1_ot
	s_waitcnt vmcnt(15)
	v_cvt_pk_f32_fp8_e32 v[120:121], v8
	v_cvt_pk_f32_fp8_sdwa v[122:123], v8 src0_sel:WORD_1
	v_cvt_pk_f32_fp8_e32 v[124:125], v9
	v_cvt_pk_f32_fp8_sdwa v[126:127], v9 src0_sel:WORD_1
	v_pk_fma_f32 v[156:157], v[120:121], v[140:141], v[156:157] op_sel_hi:[1,0,1]
	v_pk_fma_f32 v[158:159], v[122:123], v[140:141], v[158:159] op_sel_hi:[1,0,1]
	v_pk_fma_f32 v[160:161], v[124:125], v[140:141], v[160:161] op_sel_hi:[1,0,1]
	v_pk_fma_f32 v[162:163], v[126:127], v[140:141], v[162:163] op_sel_hi:[1,0,1]
	v_cvt_pk_f32_fp8_e32 v[120:121], v10
	v_cvt_pk_f32_fp8_sdwa v[122:123], v10 src0_sel:WORD_1
	v_cvt_pk_f32_fp8_e32 v[124:125], v11
	v_cvt_pk_f32_fp8_sdwa v[126:127], v11 src0_sel:WORD_1
	v_pk_fma_f32 v[166:167], v[120:121], v[140:141], v[166:167] op_sel_hi:[1,0,1]
	v_pk_fma_f32 v[168:169], v[122:123], v[140:141], v[168:169] op_sel_hi:[1,0,1]
	v_pk_fma_f32 v[170:171], v[124:125], v[140:141], v[170:171] op_sel_hi:[1,0,1]
	v_pk_fma_f32 v[172:173], v[126:127], v[140:141], v[172:173] op_sel_hi:[1,0,1]
	v_lshl_add_u32 v3, v72, 7, v0
	global_load_dwordx4 v[8:11], v3, s[40:41]
	s_waitcnt vmcnt(15)
	v_cvt_pk_f32_fp8_e32 v[120:121], v12
	v_cvt_pk_f32_fp8_sdwa v[122:123], v12 src0_sel:WORD_1
	v_cvt_pk_f32_fp8_e32 v[124:125], v13
	v_cvt_pk_f32_fp8_sdwa v[126:127], v13 src0_sel:WORD_1
	v_pk_fma_f32 v[156:157], v[120:121], v[140:141], v[156:157] op_sel:[0,1,0] op_sel_hi:[1,1,1]
	v_pk_fma_f32 v[158:159], v[122:123], v[140:141], v[158:159] op_sel:[0,1,0] op_sel_hi:[1,1,1]
	v_pk_fma_f32 v[160:161], v[124:125], v[140:141], v[160:161] op_sel:[0,1,0] op_sel_hi:[1,1,1]
	v_pk_fma_f32 v[162:163], v[126:127], v[140:141], v[162:163] op_sel:[0,1,0] op_sel_hi:[1,1,1]
	v_cvt_pk_f32_fp8_e32 v[120:121], v14
	v_cvt_pk_f32_fp8_sdwa v[122:123], v14 src0_sel:WORD_1
	v_cvt_pk_f32_fp8_e32 v[124:125], v15
	v_cvt_pk_f32_fp8_sdwa v[126:127], v15 src0_sel:WORD_1
	v_pk_fma_f32 v[166:167], v[120:121], v[140:141], v[166:167] op_sel:[0,1,0] op_sel_hi:[1,1,1]
	v_pk_fma_f32 v[168:169], v[122:123], v[140:141], v[168:169] op_sel:[0,1,0] op_sel_hi:[1,1,1]
	v_pk_fma_f32 v[170:171], v[124:125], v[140:141], v[170:171] op_sel:[0,1,0] op_sel_hi:[1,1,1]
	v_pk_fma_f32 v[172:173], v[126:127], v[140:141], v[172:173] op_sel:[0,1,0] op_sel_hi:[1,1,1]
	v_lshl_add_u32 v4, v73, 7, v0
	global_load_dwordx4 v[12:15], v4, s[40:41]
	s_waitcnt vmcnt(15)
	v_cvt_pk_f32_fp8_e32 v[120:121], v16
	v_cvt_pk_f32_fp8_sdwa v[122:123], v16 src0_sel:WORD_1
	v_cvt_pk_f32_fp8_e32 v[124:125], v17
	v_cvt_pk_f32_fp8_sdwa v[126:127], v17 src0_sel:WORD_1
	v_pk_fma_f32 v[156:157], v[120:121], v[142:143], v[156:157] op_sel_hi:[1,0,1]
	v_pk_fma_f32 v[158:159], v[122:123], v[142:143], v[158:159] op_sel_hi:[1,0,1]
	v_pk_fma_f32 v[160:161], v[124:125], v[142:143], v[160:161] op_sel_hi:[1,0,1]
	v_pk_fma_f32 v[162:163], v[126:127], v[142:143], v[162:163] op_sel_hi:[1,0,1]
	v_cvt_pk_f32_fp8_e32 v[120:121], v18
	v_cvt_pk_f32_fp8_sdwa v[122:123], v18 src0_sel:WORD_1
	v_cvt_pk_f32_fp8_e32 v[124:125], v19
	v_cvt_pk_f32_fp8_sdwa v[126:127], v19 src0_sel:WORD_1
	v_pk_fma_f32 v[166:167], v[120:121], v[142:143], v[166:167] op_sel_hi:[1,0,1]
	v_pk_fma_f32 v[168:169], v[122:123], v[142:143], v[168:169] op_sel_hi:[1,0,1]
	v_pk_fma_f32 v[170:171], v[124:125], v[142:143], v[170:171] op_sel_hi:[1,0,1]
	v_pk_fma_f32 v[172:173], v[126:127], v[142:143], v[172:173] op_sel_hi:[1,0,1]
	v_lshl_add_u32 v3, v74, 7, v0
	global_load_dwordx4 v[16:19], v3, s[40:41]
	s_waitcnt vmcnt(15)
	v_cvt_pk_f32_fp8_e32 v[120:121], v20
	v_cvt_pk_f32_fp8_sdwa v[122:123], v20 src0_sel:WORD_1
	v_cvt_pk_f32_fp8_e32 v[124:125], v21
	v_cvt_pk_f32_fp8_sdwa v[126:127], v21 src0_sel:WORD_1
	v_pk_fma_f32 v[156:157], v[120:121], v[142:143], v[156:157] op_sel:[0,1,0] op_sel_hi:[1,1,1]
	v_pk_fma_f32 v[158:159], v[122:123], v[142:143], v[158:159] op_sel:[0,1,0] op_sel_hi:[1,1,1]
	v_pk_fma_f32 v[160:161], v[124:125], v[142:143], v[160:161] op_sel:[0,1,0] op_sel_hi:[1,1,1]
	v_pk_fma_f32 v[162:163], v[126:127], v[142:143], v[162:163] op_sel:[0,1,0] op_sel_hi:[1,1,1]
	v_cvt_pk_f32_fp8_e32 v[120:121], v22
	v_cvt_pk_f32_fp8_sdwa v[122:123], v22 src0_sel:WORD_1
	v_cvt_pk_f32_fp8_e32 v[124:125], v23
	v_cvt_pk_f32_fp8_sdwa v[126:127], v23 src0_sel:WORD_1
	v_pk_fma_f32 v[166:167], v[120:121], v[142:143], v[166:167] op_sel:[0,1,0] op_sel_hi:[1,1,1]
	v_pk_fma_f32 v[168:169], v[122:123], v[142:143], v[168:169] op_sel:[0,1,0] op_sel_hi:[1,1,1]
	v_pk_fma_f32 v[170:171], v[124:125], v[142:143], v[170:171] op_sel:[0,1,0] op_sel_hi:[1,1,1]
	v_pk_fma_f32 v[172:173], v[126:127], v[142:143], v[172:173] op_sel:[0,1,0] op_sel_hi:[1,1,1]
	v_lshl_add_u32 v4, v75, 7, v0
	global_load_dwordx4 v[20:23], v4, s[40:41]
	s_waitcnt vmcnt(15)
; #define FP8_LO(w) __builtin_amdgcn_cvt_pk_f32_fp8((int)(w), false)
; #define FP8_HI(w) __builtin_amdgcn_cvt_pk_f32_fp8((int)(w), true)
; DI void axpy16h(float (&acc)[16], float g, const u32x4 w) {
;     const f32x2 a0 = FP8_LO(w.x), a1 = FP8_HI(w.x), a2 = FP8_LO(w.y), a3 = FP8_HI(w.y), a4 = FP8_LO(w.z), a5 = FP8_HI(w.z), a6 = FP8_LO(w.w), a7 = FP8_HI(w.w);
;     acc[0] += g * a0.x; acc[1] += g * a0.y; acc[2] += g * a1.x; acc[3] += g * a1.y; acc[4] += g * a2.x; acc[5] += g * a2.y; acc[6] += g * a3.x; acc[7] += g * a3.y;
;     acc[8] += g * a4.x; acc[9] += g * a4.y; acc[10] += g * a5.x; acc[11] += g * a5.y; acc[12] += g * a6.x; acc[13] += g * a6.y; acc[14] += g * a7.x; acc[15] += g * a7.y;
; DI void phase_peer_v(const Args& a, int layer, int ci) {
;     ...
;                 for (int j = 0; j < 8; ++j) { const float gv = __shfl(ghs, (g8 & 7) * 8 + j); axpy16h(acc, gv, cur[j]); if (j & 1) __builtin_amdgcn_sched_barrier(0); }
	v_cvt_pk_f32_fp8_e32 v[120:121], v24
	v_cvt_pk_f32_fp8_sdwa v[122:123], v24 src0_sel:WORD_1
	v_cvt_pk_f32_fp8_e32 v[124:125], v25
	v_cvt_pk_f32_fp8_sdwa v[126:127], v25 src0_sel:WORD_1
	v_pk_fma_f32 v[156:157], v[120:121], v[144:145], v[156:157] op_sel_hi:[1,0,1]
	v_pk_fma_f32 v[158:159], v[122:123], v[144:145], v[158:159] op_sel_hi:[1,0,1]
	v_pk_fma_f32 v[160:161], v[124:125], v[144:145], v[160:161] op_sel_hi:[1,0,1]
	v_pk_fma_f32 v[162:163], v[126:127], v[144:145], v[162:163] op_sel_hi:[1,0,1]
	v_cvt_pk_f32_fp8_e32 v[120:121], v26
	v_cvt_pk_f32_fp8_sdwa v[122:123], v26 src0_sel:WORD_1
	v_cvt_pk_f32_fp8_e32 v[124:125], v27
	v_cvt_pk_f32_fp8_sdwa v[126:127], v27 src0_sel:WORD_1
	v_pk_fma_f32 v[166:167], v[120:121], v[144:145], v[166:167] op_sel_hi:[1,0,1]
	v_pk_fma_f32 v[168:169], v[122:123], v[144:145], v[168:169] op_sel_hi:[1,0,1]
	v_pk_fma_f32 v[170:171], v[124:125], v[144:145], v[170:171] op_sel_hi:[1,0,1]
	v_pk_fma_f32 v[172:173], v[126:127], v[144:145], v[172:173] op_sel_hi:[1,0,1]
	v_lshl_add_u32 v3, v76, 7, v0
	global_load_dwordx4 v[24:27], v3, s[40:41]
	s_waitcnt vmcnt(15)
	v_cvt_pk_f32_fp8_e32 v[120:121], v28
	v_cvt_pk_f32_fp8_sdwa v[122:123], v28 src0_sel:WORD_1
	v_cvt_pk_f32_fp8_e32 v[124:125], v29
	v_cvt_pk_f32_fp8_sdwa v[126:127], v29 src0_sel:WORD_1
	v_pk_fma_f32 v[156:157], v[120:121], v[144:145], v[156:157] op_sel:[0,1,0] op_sel_hi:[1,1,1]
	v_pk_fma_f32 v[158:159], v[122:123], v[144:145], v[158:159] op_sel:[0,1,0] op_sel_hi:[1,1,1]
	v_pk_fma_f32 v[160:161], v[124:125], v[144:145], v[160:161] op_sel:[0,1,0] op_sel_hi:[1,1,1]
	v_pk_fma_f32 v[162:163], v[126:127], v[144:145], v[162:163] op_sel:[0,1,0] op_sel_hi:[1,1,1]
	v_cvt_pk_f32_fp8_e32 v[120:121], v30
	v_cvt_pk_f32_fp8_sdwa v[122:123], v30 src0_sel:WORD_1
	v_cvt_pk_f32_fp8_e32 v[124:125], v31
	v_cvt_pk_f32_fp8_sdwa v[126:127], v31 src0_sel:WORD_1
	v_pk_fma_f32 v[166:167], v[120:121], v[144:145], v[166:167] op_sel:[0,1,0] op_sel_hi:[1,1,1]
	v_pk_fma_f32 v[168:169], v[122:123], v[144:145], v[168:169] op_sel:[0,1,0] op_sel_hi:[1,1,1]
	v_pk_fma_f32 v[170:171], v[124:125], v[144:145], v[170:171] op_sel:[0,1,0] op_sel_hi:[1,1,1]
	v_pk_fma_f32 v[172:173], v[126:127], v[144:145], v[172:173] op_sel:[0,1,0] op_sel_hi:[1,1,1]
	v_lshl_add_u32 v4, v77, 7, v0
	global_load_dwordx4 v[28:31], v4, s[40:41]
	s_waitcnt vmcnt(15)
	v_cvt_pk_f32_fp8_e32 v[120:121], v32
	v_cvt_pk_f32_fp8_sdwa v[122:123], v32 src0_sel:WORD_1
	v_cvt_pk_f32_fp8_e32 v[124:125], v33
	v_cvt_pk_f32_fp8_sdwa v[126:127], v33 src0_sel:WORD_1
	v_pk_fma_f32 v[156:157], v[120:121], v[146:147], v[156:157] op_sel_hi:[1,0,1]
	v_pk_fma_f32 v[158:159], v[122:123], v[146:147], v[158:159] op_sel_hi:[1,0,1]
	v_pk_fma_f32 v[160:161], v[124:125], v[146:147], v[160:161] op_sel_hi:[1,0,1]
	v_pk_fma_f32 v[162:163], v[126:127], v[146:147], v[162:163] op_sel_hi:[1,0,1]
	v_cvt_pk_f32_fp8_e32 v[120:121], v34
	v_cvt_pk_f32_fp8_sdwa v[122:123], v34 src0_sel:WORD_1
	v_cvt_pk_f32_fp8_e32 v[124:125], v35
	v_cvt_pk_f32_fp8_sdwa v[126:127], v35 src0_sel:WORD_1
	v_pk_fma_f32 v[166:167], v[120:121], v[146:147], v[166:167] op_sel_hi:[1,0,1]
	v_pk_fma_f32 v[168:169], v[122:123], v[146:147], v[168:169] op_sel_hi:[1,0,1]
	v_pk_fma_f32 v[170:171], v[124:125], v[146:147], v[170:171] op_sel_hi:[1,0,1]
	v_pk_fma_f32 v[172:173], v[126:127], v[146:147], v[172:173] op_sel_hi:[1,0,1]
	v_lshl_add_u32 v3, v78, 7, v0
	global_load_dwordx4 v[32:35], v3, s[40:41]
	s_waitcnt vmcnt(15)
	v_cvt_pk_f32_fp8_e32 v[120:121], v36
	v_cvt_pk_f32_fp8_sdwa v[122:123], v36 src0_sel:WORD_1
	v_cvt_pk_f32_fp8_e32 v[124:125], v37
	v_cvt_pk_f32_fp8_sdwa v[126:127], v37 src0_sel:WORD_1
	v_pk_fma_f32 v[156:157], v[120:121], v[146:147], v[156:157] op_sel:[0,1,0] op_sel_hi:[1,1,1]
	v_pk_fma_f32 v[158:159], v[122:123], v[146:147], v[158:159] op_sel:[0,1,0] op_sel_hi:[1,1,1]
	v_pk_fma_f32 v[160:161], v[124:125], v[146:147], v[160:161] op_sel:[0,1,0] op_sel_hi:[1,1,1]
	v_pk_fma_f32 v[162:163], v[126:127], v[146:147], v[162:163] op_sel:[0,1,0] op_sel_hi:[1,1,1]
	v_cvt_pk_f32_fp8_e32 v[120:121], v38
	v_cvt_pk_f32_fp8_sdwa v[122:123], v38 src0_sel:WORD_1
	v_cvt_pk_f32_fp8_e32 v[124:125], v39
	v_cvt_pk_f32_fp8_sdwa v[126:127], v39 src0_sel:WORD_1
	v_pk_fma_f32 v[166:167], v[120:121], v[146:147], v[166:167] op_sel:[0,1,0] op_sel_hi:[1,1,1]
	v_pk_fma_f32 v[168:169], v[122:123], v[146:147], v[168:169] op_sel:[0,1,0] op_sel_hi:[1,1,1]
	v_pk_fma_f32 v[170:171], v[124:125], v[146:147], v[170:171] op_sel:[0,1,0] op_sel_hi:[1,1,1]
	v_pk_fma_f32 v[172:173], v[126:127], v[146:147], v[172:173] op_sel:[0,1,0] op_sel_hi:[1,1,1]
	v_lshl_add_u32 v4, v79, 7, v0
	global_load_dwordx4 v[36:39], v4, s[40:41]
	s_waitcnt vmcnt(15)
	v_cvt_pk_f32_fp8_e32 v[120:121], v40
	v_cvt_pk_f32_fp8_sdwa v[122:123], v40 src0_sel:WORD_1
	v_cvt_pk_f32_fp8_e32 v[124:125], v41
	v_cvt_pk_f32_fp8_sdwa v[126:127], v41 src0_sel:WORD_1
	v_pk_fma_f32 v[156:157], v[120:121], v[148:149], v[156:157] op_sel_hi:[1,0,1]
	v_pk_fma_f32 v[158:159], v[122:123], v[148:149], v[158:159] op_sel_hi:[1,0,1]
	v_pk_fma_f32 v[160:161], v[124:125], v[148:149], v[160:161] op_sel_hi:[1,0,1]
	v_pk_fma_f32 v[162:163], v[126:127], v[148:149], v[162:163] op_sel_hi:[1,0,1]
	v_cvt_pk_f32_fp8_e32 v[120:121], v42
	v_cvt_pk_f32_fp8_sdwa v[122:123], v42 src0_sel:WORD_1
	v_cvt_pk_f32_fp8_e32 v[124:125], v43
	v_cvt_pk_f32_fp8_sdwa v[126:127], v43 src0_sel:WORD_1
	v_pk_fma_f32 v[166:167], v[120:121], v[148:149], v[166:167] op_sel_hi:[1,0,1]
	v_pk_fma_f32 v[168:169], v[122:123], v[148:149], v[168:169] op_sel_hi:[1,0,1]
	v_pk_fma_f32 v[170:171], v[124:125], v[148:149], v[170:171] op_sel_hi:[1,0,1]
	v_pk_fma_f32 v[172:173], v[126:127], v[148:149], v[172:173] op_sel_hi:[1,0,1]
	v_lshl_add_u32 v3, v80, 7, v0
	global_load_dwordx4 v[40:43], v3, s[40:41]
	s_waitcnt vmcnt(15)
; #define FP8_LO(w) __builtin_amdgcn_cvt_pk_f32_fp8((int)(w), false)
; #define FP8_HI(w) __builtin_amdgcn_cvt_pk_f32_fp8((int)(w), true)
; DI void axpy16h(float (&acc)[16], float g, const u32x4 w) {
;     const f32x2 a0 = FP8_LO(w.x), a1 = FP8_HI(w.x), a2 = FP8_LO(w.y), a3 = FP8_HI(w.y), a4 = FP8_LO(w.z), a5 = FP8_HI(w.z), a6 = FP8_LO(w.w), a7 = FP8_HI(w.w);
;     acc[0] += g * a0.x; acc[1] += g * a0.y; acc[2] += g * a1.x; acc[3] += g * a1.y; acc[4] += g * a2.x; acc[5] += g * a2.y; acc[6] += g * a3.x; acc[7] += g * a3.y;
;     acc[8] += g * a4.x; acc[9] += g * a4.y; acc[10] += g * a5.x; acc[11] += g * a5.y; acc[12] += g * a6.x; acc[13] += g * a6.y; acc[14] += g * a7.x; acc[15] += g * a7.y;
; DI void phase_peer_v(const Args& a, int layer, int ci) {
;     ...
;                 for (int j = 0; j < 8; ++j) { const float gv = __shfl(ghs, (g8 & 7) * 8 + j); axpy16h(acc, gv, cur[j]); if (j & 1) __builtin_amdgcn_sched_barrier(0); }
	v_cvt_pk_f32_fp8_e32 v[120:121], v44
	v_cvt_pk_f32_fp8_sdwa v[122:123], v44 src0_sel:WORD_1
	v_cvt_pk_f32_fp8_e32 v[124:125], v45
	v_cvt_pk_f32_fp8_sdwa v[126:127], v45 src0_sel:WORD_1
	v_pk_fma_f32 v[156:157], v[120:121], v[148:149], v[156:157] op_sel:[0,1,0] op_sel_hi:[1,1,1]
	v_pk_fma_f32 v[158:159], v[122:123], v[148:149], v[158:159] op_sel:[0,1,0] op_sel_hi:[1,1,1]
	v_pk_fma_f32 v[160:161], v[124:125], v[148:149], v[160:161] op_sel:[0,1,0] op_sel_hi:[1,1,1]
	v_pk_fma_f32 v[162:163], v[126:127], v[148:149], v[162:163] op_sel:[0,1,0] op_sel_hi:[1,1,1]
	v_cvt_pk_f32_fp8_e32 v[120:121], v46
	v_cvt_pk_f32_fp8_sdwa v[122:123], v46 src0_sel:WORD_1
	v_cvt_pk_f32_fp8_e32 v[124:125], v47
	v_cvt_pk_f32_fp8_sdwa v[126:127], v47 src0_sel:WORD_1
	v_pk_fma_f32 v[166:167], v[120:121], v[148:149], v[166:167] op_sel:[0,1,0] op_sel_hi:[1,1,1]
	v_pk_fma_f32 v[168:169], v[122:123], v[148:149], v[168:169] op_sel:[0,1,0] op_sel_hi:[1,1,1]
	v_pk_fma_f32 v[170:171], v[124:125], v[148:149], v[170:171] op_sel:[0,1,0] op_sel_hi:[1,1,1]
	v_pk_fma_f32 v[172:173], v[126:127], v[148:149], v[172:173] op_sel:[0,1,0] op_sel_hi:[1,1,1]
	v_lshl_add_u32 v4, v81, 7, v0
	global_load_dwordx4 v[44:47], v4, s[40:41]
	s_waitcnt vmcnt(15)
	v_cvt_pk_f32_fp8_e32 v[120:121], v48
	v_cvt_pk_f32_fp8_sdwa v[122:123], v48 src0_sel:WORD_1
	v_cvt_pk_f32_fp8_e32 v[124:125], v49
	v_cvt_pk_f32_fp8_sdwa v[126:127], v49 src0_sel:WORD_1
	v_pk_fma_f32 v[156:157], v[120:121], v[150:151], v[156:157] op_sel_hi:[1,0,1]
	v_pk_fma_f32 v[158:159], v[122:123], v[150:151], v[158:159] op_sel_hi:[1,0,1]
	v_pk_fma_f32 v[160:161], v[124:125], v[150:151], v[160:161] op_sel_hi:[1,0,1]
	v_pk_fma_f32 v[162:163], v[126:127], v[150:151], v[162:163] op_sel_hi:[1,0,1]
	v_cvt_pk_f32_fp8_e32 v[120:121], v50
	v_cvt_pk_f32_fp8_sdwa v[122:123], v50 src0_sel:WORD_1
	v_cvt_pk_f32_fp8_e32 v[124:125], v51
	v_cvt_pk_f32_fp8_sdwa v[126:127], v51 src0_sel:WORD_1
	v_pk_fma_f32 v[166:167], v[120:121], v[150:151], v[166:167] op_sel_hi:[1,0,1]
	v_pk_fma_f32 v[168:169], v[122:123], v[150:151], v[168:169] op_sel_hi:[1,0,1]
	v_pk_fma_f32 v[170:171], v[124:125], v[150:151], v[170:171] op_sel_hi:[1,0,1]
	v_pk_fma_f32 v[172:173], v[126:127], v[150:151], v[172:173] op_sel_hi:[1,0,1]
	v_lshl_add_u32 v3, v82, 7, v0
	global_load_dwordx4 v[48:51], v3, s[40:41]
	s_waitcnt vmcnt(15)
	v_cvt_pk_f32_fp8_e32 v[120:121], v52
	v_cvt_pk_f32_fp8_sdwa v[122:123], v52 src0_sel:WORD_1
	v_cvt_pk_f32_fp8_e32 v[124:125], v53
	v_cvt_pk_f32_fp8_sdwa v[126:127], v53 src0_sel:WORD_1
	v_pk_fma_f32 v[156:157], v[120:121], v[150:151], v[156:157] op_sel:[0,1,0] op_sel_hi:[1,1,1]
	v_pk_fma_f32 v[158:159], v[122:123], v[150:151], v[158:159] op_sel:[0,1,0] op_sel_hi:[1,1,1]
	v_pk_fma_f32 v[160:161], v[124:125], v[150:151], v[160:161] op_sel:[0,1,0] op_sel_hi:[1,1,1]
	v_pk_fma_f32 v[162:163], v[126:127], v[150:151], v[162:163] op_sel:[0,1,0] op_sel_hi:[1,1,1]
	v_cvt_pk_f32_fp8_e32 v[120:121], v54
	v_cvt_pk_f32_fp8_sdwa v[122:123], v54 src0_sel:WORD_1
	v_cvt_pk_f32_fp8_e32 v[124:125], v55
	v_cvt_pk_f32_fp8_sdwa v[126:127], v55 src0_sel:WORD_1
	v_pk_fma_f32 v[166:167], v[120:121], v[150:151], v[166:167] op_sel:[0,1,0] op_sel_hi:[1,1,1]
	v_pk_fma_f32 v[168:169], v[122:123], v[150:151], v[168:169] op_sel:[0,1,0] op_sel_hi:[1,1,1]
	v_pk_fma_f32 v[170:171], v[124:125], v[150:151], v[170:171] op_sel:[0,1,0] op_sel_hi:[1,1,1]
	v_pk_fma_f32 v[172:173], v[126:127], v[150:151], v[172:173] op_sel:[0,1,0] op_sel_hi:[1,1,1]
	v_lshl_add_u32 v4, v83, 7, v0
	global_load_dwordx4 v[52:55], v4, s[40:41]
	s_waitcnt vmcnt(15)
	v_cvt_pk_f32_fp8_e32 v[120:121], v56
	v_cvt_pk_f32_fp8_sdwa v[122:123], v56 src0_sel:WORD_1
	v_cvt_pk_f32_fp8_e32 v[124:125], v57
	v_cvt_pk_f32_fp8_sdwa v[126:127], v57 src0_sel:WORD_1
	v_pk_fma_f32 v[156:157], v[120:121], v[152:153], v[156:157] op_sel_hi:[1,0,1]
	v_pk_fma_f32 v[158:159], v[122:123], v[152:153], v[158:159] op_sel_hi:[1,0,1]
	v_pk_fma_f32 v[160:161], v[124:125], v[152:153], v[160:161] op_sel_hi:[1,0,1]
	v_pk_fma_f32 v[162:163], v[126:127], v[152:153], v[162:163] op_sel_hi:[1,0,1]
	v_cvt_pk_f32_fp8_e32 v[120:121], v58
	v_cvt_pk_f32_fp8_sdwa v[122:123], v58 src0_sel:WORD_1
	v_cvt_pk_f32_fp8_e32 v[124:125], v59
	v_cvt_pk_f32_fp8_sdwa v[126:127], v59 src0_sel:WORD_1
	v_pk_fma_f32 v[166:167], v[120:121], v[152:153], v[166:167] op_sel_hi:[1,0,1]
	v_pk_fma_f32 v[168:169], v[122:123], v[152:153], v[168:169] op_sel_hi:[1,0,1]
	v_pk_fma_f32 v[170:171], v[124:125], v[152:153], v[170:171] op_sel_hi:[1,0,1]
	v_pk_fma_f32 v[172:173], v[126:127], v[152:153], v[172:173] op_sel_hi:[1,0,1]
	v_lshl_add_u32 v3, v84, 7, v0
	global_load_dwordx4 v[56:59], v3, s[40:41]
	s_waitcnt vmcnt(15)
	v_cvt_pk_f32_fp8_e32 v[120:121], v60
	v_cvt_pk_f32_fp8_sdwa v[122:123], v60 src0_sel:WORD_1
	v_cvt_pk_f32_fp8_e32 v[124:125], v61
	v_cvt_pk_f32_fp8_sdwa v[126:127], v61 src0_sel:WORD_1
	v_pk_fma_f32 v[156:157], v[120:121], v[152:153], v[156:157] op_sel:[0,1,0] op_sel_hi:[1,1,1]
	v_pk_fma_f32 v[158:159], v[122:123], v[152:153], v[158:159] op_sel:[0,1,0] op_sel_hi:[1,1,1]
	v_pk_fma_f32 v[160:161], v[124:125], v[152:153], v[160:161] op_sel:[0,1,0] op_sel_hi:[1,1,1]
	v_pk_fma_f32 v[162:163], v[126:127], v[152:153], v[162:163] op_sel:[0,1,0] op_sel_hi:[1,1,1]
	v_cvt_pk_f32_fp8_e32 v[120:121], v62
	v_cvt_pk_f32_fp8_sdwa v[122:123], v62 src0_sel:WORD_1
	v_cvt_pk_f32_fp8_e32 v[124:125], v63
	v_cvt_pk_f32_fp8_sdwa v[126:127], v63 src0_sel:WORD_1
	v_pk_fma_f32 v[166:167], v[120:121], v[152:153], v[166:167] op_sel:[0,1,0] op_sel_hi:[1,1,1]
	v_pk_fma_f32 v[168:169], v[122:123], v[152:153], v[168:169] op_sel:[0,1,0] op_sel_hi:[1,1,1]
	v_pk_fma_f32 v[170:171], v[124:125], v[152:153], v[170:171] op_sel:[0,1,0] op_sel_hi:[1,1,1]
	v_pk_fma_f32 v[172:173], v[126:127], v[152:153], v[172:173] op_sel:[0,1,0] op_sel_hi:[1,1,1]
	v_lshl_add_u32 v4, v85, 7, v0
	global_load_dwordx4 v[60:63], v4, s[40:41]
	s_waitcnt vmcnt(15)
; #define FP8_LO(w) __builtin_amdgcn_cvt_pk_f32_fp8((int)(w), false)
; #define FP8_HI(w) __builtin_amdgcn_cvt_pk_f32_fp8((int)(w), true)
; DI void axpy16h(float (&acc)[16], float g, const u32x4 w) {
;     const f32x2 a0 = FP8_LO(w.x), a1 = FP8_HI(w.x), a2 = FP8_LO(w.y), a3 = FP8_HI(w.y), a4 = FP8_LO(w.z), a5 = FP8_HI(w.z), a6 = FP8_LO(w.w), a7 = FP8_HI(w.w);
;     acc[0] += g * a0.x; acc[1] += g * a0.y; acc[2] += g * a1.x; acc[3] += g * a1.y; acc[4] += g * a2.x; acc[5] += g * a2.y; acc[6] += g * a3.x; acc[7] += g * a3.y;
;     acc[8] += g * a4.x; acc[9] += g * a4.y; acc[10] += g * a5.x; acc[11] += g * a5.y; acc[12] += g * a6.x; acc[13] += g * a6.y; acc[14] += g * a7.x; acc[15] += g * a7.y;
; DI void phase_peer_v(const Args& a, int layer, int ci) {
;     ...
;                 for (int j = 0; j < 8; ++j) { const float gv = __shfl(ghs, (g8 & 7) * 8 + j); axpy16h(acc, gv, cur[j]); if (j & 1) __builtin_amdgcn_sched_barrier(0); }
	v_cvt_pk_f32_fp8_e32 v[120:121], v64
	v_cvt_pk_f32_fp8_sdwa v[122:123], v64 src0_sel:WORD_1
	v_cvt_pk_f32_fp8_e32 v[124:125], v65
	v_cvt_pk_f32_fp8_sdwa v[126:127], v65 src0_sel:WORD_1
	v_pk_fma_f32 v[156:157], v[120:121], v[154:155], v[156:157] op_sel_hi:[1,0,1]
	v_pk_fma_f32 v[158:159], v[122:123], v[154:155], v[158:159] op_sel_hi:[1,0,1]
	v_pk_fma_f32 v[160:161], v[124:125], v[154:155], v[160:161] op_sel_hi:[1,0,1]
	v_pk_fma_f32 v[162:163], v[126:127], v[154:155], v[162:163] op_sel_hi:[1,0,1]
	v_cvt_pk_f32_fp8_e32 v[120:121], v66
	v_cvt_pk_f32_fp8_sdwa v[122:123], v66 src0_sel:WORD_1
	v_cvt_pk_f32_fp8_e32 v[124:125], v67
	v_cvt_pk_f32_fp8_sdwa v[126:127], v67 src0_sel:WORD_1
	v_pk_fma_f32 v[166:167], v[120:121], v[154:155], v[166:167] op_sel_hi:[1,0,1]
	v_pk_fma_f32 v[168:169], v[122:123], v[154:155], v[168:169] op_sel_hi:[1,0,1]
	v_pk_fma_f32 v[170:171], v[124:125], v[154:155], v[170:171] op_sel_hi:[1,0,1]
	v_pk_fma_f32 v[172:173], v[126:127], v[154:155], v[172:173] op_sel_hi:[1,0,1]
	v_lshl_add_u32 v3, v86, 7, v0
	global_load_dwordx4 v[64:67], v3, s[40:41]
	s_waitcnt vmcnt(15)
	v_cvt_pk_f32_fp8_e32 v[120:121], v68
	v_cvt_pk_f32_fp8_sdwa v[122:123], v68 src0_sel:WORD_1
	v_cvt_pk_f32_fp8_e32 v[124:125], v69
	v_cvt_pk_f32_fp8_sdwa v[126:127], v69 src0_sel:WORD_1
	v_pk_fma_f32 v[156:157], v[120:121], v[154:155], v[156:157] op_sel:[0,1,0] op_sel_hi:[1,1,1]
	v_pk_fma_f32 v[158:159], v[122:123], v[154:155], v[158:159] op_sel:[0,1,0] op_sel_hi:[1,1,1]
	v_pk_fma_f32 v[160:161], v[124:125], v[154:155], v[160:161] op_sel:[0,1,0] op_sel_hi:[1,1,1]
	v_pk_fma_f32 v[162:163], v[126:127], v[154:155], v[162:163] op_sel:[0,1,0] op_sel_hi:[1,1,1]
	v_cvt_pk_f32_fp8_e32 v[120:121], v70
	v_cvt_pk_f32_fp8_sdwa v[122:123], v70 src0_sel:WORD_1
	v_cvt_pk_f32_fp8_e32 v[124:125], v71
	v_cvt_pk_f32_fp8_sdwa v[126:127], v71 src0_sel:WORD_1
	v_pk_fma_f32 v[166:167], v[120:121], v[154:155], v[166:167] op_sel:[0,1,0] op_sel_hi:[1,1,1]
	v_pk_fma_f32 v[168:169], v[122:123], v[154:155], v[168:169] op_sel:[0,1,0] op_sel_hi:[1,1,1]
	v_pk_fma_f32 v[170:171], v[124:125], v[154:155], v[170:171] op_sel:[0,1,0] op_sel_hi:[1,1,1]
	v_pk_fma_f32 v[172:173], v[126:127], v[154:155], v[172:173] op_sel:[0,1,0] op_sel_hi:[1,1,1]
	v_lshl_add_u32 v4, v87, 7, v0
	global_load_dwordx4 v[68:71], v4, s[40:41]
	s_branch .Lpv_b1_nost
.Lpv_b1_ot:
	s_waitcnt vmcnt(19)
	v_cvt_pk_f32_fp8_e32 v[120:121], v8
	v_cvt_pk_f32_fp8_sdwa v[122:123], v8 src0_sel:WORD_1
	v_cvt_pk_f32_fp8_e32 v[124:125], v9
	v_cvt_pk_f32_fp8_sdwa v[126:127], v9 src0_sel:WORD_1
	v_pk_fma_f32 v[156:157], v[120:121], v[140:141], v[156:157] op_sel_hi:[1,0,1]
	v_pk_fma_f32 v[158:159], v[122:123], v[140:141], v[158:159] op_sel_hi:[1,0,1]
	v_pk_fma_f32 v[160:161], v[124:125], v[140:141], v[160:161] op_sel_hi:[1,0,1]
	v_pk_fma_f32 v[162:163], v[126:127], v[140:141], v[162:163] op_sel_hi:[1,0,1]
	v_cvt_pk_f32_fp8_e32 v[120:121], v10
	v_cvt_pk_f32_fp8_sdwa v[122:123], v10 src0_sel:WORD_1
	v_cvt_pk_f32_fp8_e32 v[124:125], v11
	v_cvt_pk_f32_fp8_sdwa v[126:127], v11 src0_sel:WORD_1
	v_pk_fma_f32 v[166:167], v[120:121], v[140:141], v[166:167] op_sel_hi:[1,0,1]
	v_pk_fma_f32 v[168:169], v[122:123], v[140:141], v[168:169] op_sel_hi:[1,0,1]
	v_pk_fma_f32 v[170:171], v[124:125], v[140:141], v[170:171] op_sel_hi:[1,0,1]
	v_pk_fma_f32 v[172:173], v[126:127], v[140:141], v[172:173] op_sel_hi:[1,0,1]
	v_lshl_add_u32 v3, v72, 7, v0
	global_load_dwordx4 v[8:11], v3, s[40:41]
	s_waitcnt vmcnt(19)
	v_cvt_pk_f32_fp8_e32 v[120:121], v12
	v_cvt_pk_f32_fp8_sdwa v[122:123], v12 src0_sel:WORD_1
	v_cvt_pk_f32_fp8_e32 v[124:125], v13
	v_cvt_pk_f32_fp8_sdwa v[126:127], v13 src0_sel:WORD_1
	v_pk_fma_f32 v[156:157], v[120:121], v[140:141], v[156:157] op_sel:[0,1,0] op_sel_hi:[1,1,1]
	v_pk_fma_f32 v[158:159], v[122:123], v[140:141], v[158:159] op_sel:[0,1,0] op_sel_hi:[1,1,1]
	v_pk_fma_f32 v[160:161], v[124:125], v[140:141], v[160:161] op_sel:[0,1,0] op_sel_hi:[1,1,1]
	v_pk_fma_f32 v[162:163], v[126:127], v[140:141], v[162:163] op_sel:[0,1,0] op_sel_hi:[1,1,1]
	v_cvt_pk_f32_fp8_e32 v[120:121], v14
	v_cvt_pk_f32_fp8_sdwa v[122:123], v14 src0_sel:WORD_1
	v_cvt_pk_f32_fp8_e32 v[124:125], v15
	v_cvt_pk_f32_fp8_sdwa v[126:127], v15 src0_sel:WORD_1
	v_pk_fma_f32 v[166:167], v[120:121], v[140:141], v[166:167] op_sel:[0,1,0] op_sel_hi:[1,1,1]
	v_pk_fma_f32 v[168:169], v[122:123], v[140:141], v[168:169] op_sel:[0,1,0] op_sel_hi:[1,1,1]
	v_pk_fma_f32 v[170:171], v[124:125], v[140:141], v[170:171] op_sel:[0,1,0] op_sel_hi:[1,1,1]
	v_pk_fma_f32 v[172:173], v[126:127], v[140:141], v[172:173] op_sel:[0,1,0] op_sel_hi:[1,1,1]
	v_lshl_add_u32 v4, v73, 7, v0
	global_load_dwordx4 v[12:15], v4, s[40:41]
	s_waitcnt vmcnt(19)
	v_cvt_pk_f32_fp8_e32 v[120:121], v16
	v_cvt_pk_f32_fp8_sdwa v[122:123], v16 src0_sel:WORD_1
	v_cvt_pk_f32_fp8_e32 v[124:125], v17
	v_cvt_pk_f32_fp8_sdwa v[126:127], v17 src0_sel:WORD_1
	v_pk_fma_f32 v[156:157], v[120:121], v[142:143], v[156:157] op_sel_hi:[1,0,1]
	v_pk_fma_f32 v[158:159], v[122:123], v[142:143], v[158:159] op_sel_hi:[1,0,1]
	v_pk_fma_f32 v[160:161], v[124:125], v[142:143], v[160:161] op_sel_hi:[1,0,1]
	v_pk_fma_f32 v[162:163], v[126:127], v[142:143], v[162:163] op_sel_hi:[1,0,1]
	v_cvt_pk_f32_fp8_e32 v[120:121], v18
	v_cvt_pk_f32_fp8_sdwa v[122:123], v18 src0_sel:WORD_1
	v_cvt_pk_f32_fp8_e32 v[124:125], v19
	v_cvt_pk_f32_fp8_sdwa v[126:127], v19 src0_sel:WORD_1
	v_pk_fma_f32 v[166:167], v[120:121], v[142:143], v[166:167] op_sel_hi:[1,0,1]
	v_pk_fma_f32 v[168:169], v[122:123], v[142:143], v[168:169] op_sel_hi:[1,0,1]
	v_pk_fma_f32 v[170:171], v[124:125], v[142:143], v[170:171] op_sel_hi:[1,0,1]
	v_pk_fma_f32 v[172:173], v[126:127], v[142:143], v[172:173] op_sel_hi:[1,0,1]
	v_lshl_add_u32 v3, v74, 7, v0
	global_load_dwordx4 v[16:19], v3, s[40:41]
	s_waitcnt vmcnt(19)
; #define FP8_LO(w) __builtin_amdgcn_cvt_pk_f32_fp8((int)(w), false)
; #define FP8_HI(w) __builtin_amdgcn_cvt_pk_f32_fp8((int)(w), true)
; DI void axpy16h(float (&acc)[16], float g, const u32x4 w) {
;     const f32x2 a0 = FP8_LO(w.x), a1 = FP8_HI(w.x), a2 = FP8_LO(w.y), a3 = FP8_HI(w.y), a4 = FP8_LO(w.z), a5 = FP8_HI(w.z), a6 = FP8_LO(w.w), a7 = FP8_HI(w.w);
;     acc[0] += g * a0.x; acc[1] += g * a0.y; acc[2] += g * a1.x; acc[3] += g * a1.y; acc[4] += g * a2.x; acc[5] += g * a2.y; acc[6] += g * a3.x; acc[7] += g * a3.y;
;     acc[8] += g * a4.x; acc[9] += g * a4.y; acc[10] += g * a5.x; acc[11] += g * a5.y; acc[12] += g * a6.x; acc[13] += g * a6.y; acc[14] += g * a7.x; acc[15] += g * a7.y;
; DI void phase_peer_v(const Args& a, int layer, int ci) {
;     ...
;                 for (int j = 0; j < 8; ++j) { const float gv = __shfl(ghs, (g8 & 7) * 8 + j); axpy16h(acc, gv, cur[j]); if (j & 1) __builtin_amdgcn_sched_barrier(0); }
	v_cvt_pk_f32_fp8_e32 v[120:121], v20
	v_cvt_pk_f32_fp8_sdwa v[122:123], v20 src0_sel:WORD_1
	v_cvt_pk_f32_fp8_e32 v[124:125], v21
	v_cvt_pk_f32_fp8_sdwa v[126:127], v21 src0_sel:WORD_1
	v_pk_fma_f32 v[156:157], v[120:121], v[142:143], v[156:157] op_sel:[0,1,0] op_sel_hi:[1,1,1]
	v_pk_fma_f32 v[158:159], v[122:123], v[142:143], v[158:159] op_sel:[0,1,0] op_sel_hi:[1,1,1]
	v_pk_fma_f32 v[160:161], v[124:125], v[142:143], v[160:161] op_sel:[0,1,0] op_sel_hi:[1,1,1]
	v_pk_fma_f32 v[162:163], v[126:127], v[142:143], v[162:163] op_sel:[0,1,0] op_sel_hi:[1,1,1]
	v_cvt_pk_f32_fp8_e32 v[120:121], v22
	v_cvt_pk_f32_fp8_sdwa v[122:123], v22 src0_sel:WORD_1
	v_cvt_pk_f32_fp8_e32 v[124:125], v23
	v_cvt_pk_f32_fp8_sdwa v[126:127], v23 src0_sel:WORD_1
	v_pk_fma_f32 v[166:167], v[120:121], v[142:143], v[166:167] op_sel:[0,1,0] op_sel_hi:[1,1,1]
	v_pk_fma_f32 v[168:169], v[122:123], v[142:143], v[168:169] op_sel:[0,1,0] op_sel_hi:[1,1,1]
	v_pk_fma_f32 v[170:171], v[124:125], v[142:143], v[170:171] op_sel:[0,1,0] op_sel_hi:[1,1,1]
	v_pk_fma_f32 v[172:173], v[126:127], v[142:143], v[172:173] op_sel:[0,1,0] op_sel_hi:[1,1,1]
	v_lshl_add_u32 v4, v75, 7, v0
	global_load_dwordx4 v[20:23], v4, s[40:41]
	s_waitcnt vmcnt(19)
	v_cvt_pk_f32_fp8_e32 v[120:121], v24
	v_cvt_pk_f32_fp8_sdwa v[122:123], v24 src0_sel:WORD_1
	v_cvt_pk_f32_fp8_e32 v[124:125], v25
	v_cvt_pk_f32_fp8_sdwa v[126:127], v25 src0_sel:WORD_1
	v_pk_fma_f32 v[156:157], v[120:121], v[144:145], v[156:157] op_sel_hi:[1,0,1]
	v_pk_fma_f32 v[158:159], v[122:123], v[144:145], v[158:159] op_sel_hi:[1,0,1]
	v_pk_fma_f32 v[160:161], v[124:125], v[144:145], v[160:161] op_sel_hi:[1,0,1]
	v_pk_fma_f32 v[162:163], v[126:127], v[144:145], v[162:163] op_sel_hi:[1,0,1]
	v_cvt_pk_f32_fp8_e32 v[120:121], v26
	v_cvt_pk_f32_fp8_sdwa v[122:123], v26 src0_sel:WORD_1
	v_cvt_pk_f32_fp8_e32 v[124:125], v27
	v_cvt_pk_f32_fp8_sdwa v[126:127], v27 src0_sel:WORD_1
	v_pk_fma_f32 v[166:167], v[120:121], v[144:145], v[166:167] op_sel_hi:[1,0,1]
	v_pk_fma_f32 v[168:169], v[122:123], v[144:145], v[168:169] op_sel_hi:[1,0,1]
	v_pk_fma_f32 v[170:171], v[124:125], v[144:145], v[170:171] op_sel_hi:[1,0,1]
	v_pk_fma_f32 v[172:173], v[126:127], v[144:145], v[172:173] op_sel_hi:[1,0,1]
	v_lshl_add_u32 v3, v76, 7, v0
	global_load_dwordx4 v[24:27], v3, s[40:41]
	s_waitcnt vmcnt(19)
	v_cvt_pk_f32_fp8_e32 v[120:121], v28
	v_cvt_pk_f32_fp8_sdwa v[122:123], v28 src0_sel:WORD_1
	v_cvt_pk_f32_fp8_e32 v[124:125], v29
	v_cvt_pk_f32_fp8_sdwa v[126:127], v29 src0_sel:WORD_1
	v_pk_fma_f32 v[156:157], v[120:121], v[144:145], v[156:157] op_sel:[0,1,0] op_sel_hi:[1,1,1]
	v_pk_fma_f32 v[158:159], v[122:123], v[144:145], v[158:159] op_sel:[0,1,0] op_sel_hi:[1,1,1]
	v_pk_fma_f32 v[160:161], v[124:125], v[144:145], v[160:161] op_sel:[0,1,0] op_sel_hi:[1,1,1]
	v_pk_fma_f32 v[162:163], v[126:127], v[144:145], v[162:163] op_sel:[0,1,0] op_sel_hi:[1,1,1]
	v_cvt_pk_f32_fp8_e32 v[120:121], v30
	v_cvt_pk_f32_fp8_sdwa v[122:123], v30 src0_sel:WORD_1
	v_cvt_pk_f32_fp8_e32 v[124:125], v31
	v_cvt_pk_f32_fp8_sdwa v[126:127], v31 src0_sel:WORD_1
	v_pk_fma_f32 v[166:167], v[120:121], v[144:145], v[166:167] op_sel:[0,1,0] op_sel_hi:[1,1,1]
	v_pk_fma_f32 v[168:169], v[122:123], v[144:145], v[168:169] op_sel:[0,1,0] op_sel_hi:[1,1,1]
	v_pk_fma_f32 v[170:171], v[124:125], v[144:145], v[170:171] op_sel:[0,1,0] op_sel_hi:[1,1,1]
	v_pk_fma_f32 v[172:173], v[126:127], v[144:145], v[172:173] op_sel:[0,1,0] op_sel_hi:[1,1,1]
	v_lshl_add_u32 v4, v77, 7, v0
	global_load_dwordx4 v[28:31], v4, s[40:41]
	s_waitcnt vmcnt(19)
	v_cvt_pk_f32_fp8_e32 v[120:121], v32
	v_cvt_pk_f32_fp8_sdwa v[122:123], v32 src0_sel:WORD_1
	v_cvt_pk_f32_fp8_e32 v[124:125], v33
	v_cvt_pk_f32_fp8_sdwa v[126:127], v33 src0_sel:WORD_1
	v_pk_fma_f32 v[156:157], v[120:121], v[146:147], v[156:157] op_sel_hi:[1,0,1]
	v_pk_fma_f32 v[158:159], v[122:123], v[146:147], v[158:159] op_sel_hi:[1,0,1]
	v_pk_fma_f32 v[160:161], v[124:125], v[146:147], v[160:161] op_sel_hi:[1,0,1]
	v_pk_fma_f32 v[162:163], v[126:127], v[146:147], v[162:163] op_sel_hi:[1,0,1]
	v_cvt_pk_f32_fp8_e32 v[120:121], v34
	v_cvt_pk_f32_fp8_sdwa v[122:123], v34 src0_sel:WORD_1
	v_cvt_pk_f32_fp8_e32 v[124:125], v35
	v_cvt_pk_f32_fp8_sdwa v[126:127], v35 src0_sel:WORD_1
	v_pk_fma_f32 v[166:167], v[120:121], v[146:147], v[166:167] op_sel_hi:[1,0,1]
	v_pk_fma_f32 v[168:169], v[122:123], v[146:147], v[168:169] op_sel_hi:[1,0,1]
	v_pk_fma_f32 v[170:171], v[124:125], v[146:147], v[170:171] op_sel_hi:[1,0,1]
	v_pk_fma_f32 v[172:173], v[126:127], v[146:147], v[172:173] op_sel_hi:[1,0,1]
	v_lshl_add_u32 v3, v78, 7, v0
	global_load_dwordx4 v[32:35], v3, s[40:41]
	s_waitcnt vmcnt(19)
	v_cvt_pk_f32_fp8_e32 v[120:121], v36
	v_cvt_pk_f32_fp8_sdwa v[122:123], v36 src0_sel:WORD_1
	v_cvt_pk_f32_fp8_e32 v[124:125], v37
	v_cvt_pk_f32_fp8_sdwa v[126:127], v37 src0_sel:WORD_1
	v_pk_fma_f32 v[156:157], v[120:121], v[146:147], v[156:157] op_sel:[0,1,0] op_sel_hi:[1,1,1]
	v_pk_fma_f32 v[158:159], v[122:123], v[146:147], v[158:159] op_sel:[0,1,0] op_sel_hi:[1,1,1]
	v_pk_fma_f32 v[160:161], v[124:125], v[146:147], v[160:161] op_sel:[0,1,0] op_sel_hi:[1,1,1]
	v_pk_fma_f32 v[162:163], v[126:127], v[146:147], v[162:163] op_sel:[0,1,0] op_sel_hi:[1,1,1]
	v_cvt_pk_f32_fp8_e32 v[120:121], v38
	v_cvt_pk_f32_fp8_sdwa v[122:123], v38 src0_sel:WORD_1
	v_cvt_pk_f32_fp8_e32 v[124:125], v39
	v_cvt_pk_f32_fp8_sdwa v[126:127], v39 src0_sel:WORD_1
	v_pk_fma_f32 v[166:167], v[120:121], v[146:147], v[166:167] op_sel:[0,1,0] op_sel_hi:[1,1,1]
	v_pk_fma_f32 v[168:169], v[122:123], v[146:147], v[168:169] op_sel:[0,1,0] op_sel_hi:[1,1,1]
	v_pk_fma_f32 v[170:171], v[124:125], v[146:147], v[170:171] op_sel:[0,1,0] op_sel_hi:[1,1,1]
	v_pk_fma_f32 v[172:173], v[126:127], v[146:147], v[172:173] op_sel:[0,1,0] op_sel_hi:[1,1,1]
	v_lshl_add_u32 v4, v79, 7, v0
	global_load_dwordx4 v[36:39], v4, s[40:41]
	s_waitcnt vmcnt(19)
; #define FP8_LO(w) __builtin_amdgcn_cvt_pk_f32_fp8((int)(w), false)
; #define FP8_HI(w) __builtin_amdgcn_cvt_pk_f32_fp8((int)(w), true)
; DI void axpy16h(float (&acc)[16], float g, const u32x4 w) {
;     const f32x2 a0 = FP8_LO(w.x), a1 = FP8_HI(w.x), a2 = FP8_LO(w.y), a3 = FP8_HI(w.y), a4 = FP8_LO(w.z), a5 = FP8_HI(w.z), a6 = FP8_LO(w.w), a7 = FP8_HI(w.w);
;     acc[0] += g * a0.x; acc[1] += g * a0.y; acc[2] += g * a1.x; acc[3] += g * a1.y; acc[4] += g * a2.x; acc[5] += g * a2.y; acc[6] += g * a3.x; acc[7] += g * a3.y;
;     acc[8] += g * a4.x; acc[9] += g * a4.y; acc[10] += g * a5.x; acc[11] += g * a5.y; acc[12] += g * a6.x; acc[13] += g * a6.y; acc[14] += g * a7.x; acc[15] += g * a7.y;
; DI void phase_peer_v(const Args& a, int layer, int ci) {
;     ...
;                 for (int j = 0; j < 8; ++j) { const float gv = __shfl(ghs, (g8 & 7) * 8 + j); axpy16h(acc, gv, cur[j]); if (j & 1) __builtin_amdgcn_sched_barrier(0); }
	v_cvt_pk_f32_fp8_e32 v[120:121], v40
	v_cvt_pk_f32_fp8_sdwa v[122:123], v40 src0_sel:WORD_1
	v_cvt_pk_f32_fp8_e32 v[124:125], v41
	v_cvt_pk_f32_fp8_sdwa v[126:127], v41 src0_sel:WORD_1
	v_pk_fma_f32 v[156:157], v[120:121], v[148:149], v[156:157] op_sel_hi:[1,0,1]
	v_pk_fma_f32 v[158:159], v[122:123], v[148:149], v[158:159] op_sel_hi:[1,0,1]
	v_pk_fma_f32 v[160:161], v[124:125], v[148:149], v[160:161] op_sel_hi:[1,0,1]
	v_pk_fma_f32 v[162:163], v[126:127], v[148:149], v[162:163] op_sel_hi:[1,0,1]
	v_cvt_pk_f32_fp8_e32 v[120:121], v42
	v_cvt_pk_f32_fp8_sdwa v[122:123], v42 src0_sel:WORD_1
	v_cvt_pk_f32_fp8_e32 v[124:125], v43
	v_cvt_pk_f32_fp8_sdwa v[126:127], v43 src0_sel:WORD_1
	v_pk_fma_f32 v[166:167], v[120:121], v[148:149], v[166:167] op_sel_hi:[1,0,1]
	v_pk_fma_f32 v[168:169], v[122:123], v[148:149], v[168:169] op_sel_hi:[1,0,1]
	v_pk_fma_f32 v[170:171], v[124:125], v[148:149], v[170:171] op_sel_hi:[1,0,1]
	v_pk_fma_f32 v[172:173], v[126:127], v[148:149], v[172:173] op_sel_hi:[1,0,1]
	v_lshl_add_u32 v3, v80, 7, v0
	global_load_dwordx4 v[40:43], v3, s[40:41]
	s_waitcnt vmcnt(19)
	v_cvt_pk_f32_fp8_e32 v[120:121], v44
	v_cvt_pk_f32_fp8_sdwa v[122:123], v44 src0_sel:WORD_1
	v_cvt_pk_f32_fp8_e32 v[124:125], v45
	v_cvt_pk_f32_fp8_sdwa v[126:127], v45 src0_sel:WORD_1
	v_pk_fma_f32 v[156:157], v[120:121], v[148:149], v[156:157] op_sel:[0,1,0] op_sel_hi:[1,1,1]
	v_pk_fma_f32 v[158:159], v[122:123], v[148:149], v[158:159] op_sel:[0,1,0] op_sel_hi:[1,1,1]
	v_pk_fma_f32 v[160:161], v[124:125], v[148:149], v[160:161] op_sel:[0,1,0] op_sel_hi:[1,1,1]
	v_pk_fma_f32 v[162:163], v[126:127], v[148:149], v[162:163] op_sel:[0,1,0] op_sel_hi:[1,1,1]
	v_cvt_pk_f32_fp8_e32 v[120:121], v46
	v_cvt_pk_f32_fp8_sdwa v[122:123], v46 src0_sel:WORD_1
	v_cvt_pk_f32_fp8_e32 v[124:125], v47
	v_cvt_pk_f32_fp8_sdwa v[126:127], v47 src0_sel:WORD_1
	v_pk_fma_f32 v[166:167], v[120:121], v[148:149], v[166:167] op_sel:[0,1,0] op_sel_hi:[1,1,1]
	v_pk_fma_f32 v[168:169], v[122:123], v[148:149], v[168:169] op_sel:[0,1,0] op_sel_hi:[1,1,1]
	v_pk_fma_f32 v[170:171], v[124:125], v[148:149], v[170:171] op_sel:[0,1,0] op_sel_hi:[1,1,1]
	v_pk_fma_f32 v[172:173], v[126:127], v[148:149], v[172:173] op_sel:[0,1,0] op_sel_hi:[1,1,1]
	v_lshl_add_u32 v4, v81, 7, v0
	global_load_dwordx4 v[44:47], v4, s[40:41]
	s_waitcnt vmcnt(19)
	v_cvt_pk_f32_fp8_e32 v[120:121], v48
	v_cvt_pk_f32_fp8_sdwa v[122:123], v48 src0_sel:WORD_1
	v_cvt_pk_f32_fp8_e32 v[124:125], v49
	v_cvt_pk_f32_fp8_sdwa v[126:127], v49 src0_sel:WORD_1
	v_pk_fma_f32 v[156:157], v[120:121], v[150:151], v[156:157] op_sel_hi:[1,0,1]
	v_pk_fma_f32 v[158:159], v[122:123], v[150:151], v[158:159] op_sel_hi:[1,0,1]
	v_pk_fma_f32 v[160:161], v[124:125], v[150:151], v[160:161] op_sel_hi:[1,0,1]
	v_pk_fma_f32 v[162:163], v[126:127], v[150:151], v[162:163] op_sel_hi:[1,0,1]
	v_cvt_pk_f32_fp8_e32 v[120:121], v50
	v_cvt_pk_f32_fp8_sdwa v[122:123], v50 src0_sel:WORD_1
	v_cvt_pk_f32_fp8_e32 v[124:125], v51
	v_cvt_pk_f32_fp8_sdwa v[126:127], v51 src0_sel:WORD_1
	v_pk_fma_f32 v[166:167], v[120:121], v[150:151], v[166:167] op_sel_hi:[1,0,1]
	v_pk_fma_f32 v[168:169], v[122:123], v[150:151], v[168:169] op_sel_hi:[1,0,1]
	v_pk_fma_f32 v[170:171], v[124:125], v[150:151], v[170:171] op_sel_hi:[1,0,1]
	v_pk_fma_f32 v[172:173], v[126:127], v[150:151], v[172:173] op_sel_hi:[1,0,1]
	v_lshl_add_u32 v3, v82, 7, v0
	global_load_dwordx4 v[48:51], v3, s[40:41]
	s_waitcnt vmcnt(19)
	v_cvt_pk_f32_fp8_e32 v[120:121], v52
	v_cvt_pk_f32_fp8_sdwa v[122:123], v52 src0_sel:WORD_1
	v_cvt_pk_f32_fp8_e32 v[124:125], v53
	v_cvt_pk_f32_fp8_sdwa v[126:127], v53 src0_sel:WORD_1
	v_pk_fma_f32 v[156:157], v[120:121], v[150:151], v[156:157] op_sel:[0,1,0] op_sel_hi:[1,1,1]
	v_pk_fma_f32 v[158:159], v[122:123], v[150:151], v[158:159] op_sel:[0,1,0] op_sel_hi:[1,1,1]
	v_pk_fma_f32 v[160:161], v[124:125], v[150:151], v[160:161] op_sel:[0,1,0] op_sel_hi:[1,1,1]
	v_pk_fma_f32 v[162:163], v[126:127], v[150:151], v[162:163] op_sel:[0,1,0] op_sel_hi:[1,1,1]
	v_cvt_pk_f32_fp8_e32 v[120:121], v54
	v_cvt_pk_f32_fp8_sdwa v[122:123], v54 src0_sel:WORD_1
	v_cvt_pk_f32_fp8_e32 v[124:125], v55
	v_cvt_pk_f32_fp8_sdwa v[126:127], v55 src0_sel:WORD_1
	v_pk_fma_f32 v[166:167], v[120:121], v[150:151], v[166:167] op_sel:[0,1,0] op_sel_hi:[1,1,1]
	v_pk_fma_f32 v[168:169], v[122:123], v[150:151], v[168:169] op_sel:[0,1,0] op_sel_hi:[1,1,1]
	v_pk_fma_f32 v[170:171], v[124:125], v[150:151], v[170:171] op_sel:[0,1,0] op_sel_hi:[1,1,1]
	v_pk_fma_f32 v[172:173], v[126:127], v[150:151], v[172:173] op_sel:[0,1,0] op_sel_hi:[1,1,1]
	v_lshl_add_u32 v4, v83, 7, v0
	global_load_dwordx4 v[52:55], v4, s[40:41]
	s_waitcnt vmcnt(19)
; DI void phase_peer_v(const Args& a, int layer, int ci) {
;     ...
;                 for (int j = 0; j < 8; ++j) { const float gv = __shfl(ghs, (g8 & 7) * 8 + j); axpy16h(acc, gv, cur[j]); if (j & 1) __builtin_amdgcn_sched_barrier(0); }
;     ...
;             for (int q = 0; q < 4; ++q) { const f32x4 h = *(const f32x4*)(hrow + col + 4 * q);
;                 acc[4 * q] += h.x; acc[4 * q + 1] += h.y; acc[4 * q + 2] += h.z; acc[4 * q + 3] += h.w; }
;             if (ci == 0) {
; #pragma unroll
;                 for (int q = 0; q < 4; ++q) { f32x4 h; h.x = acc[4 * q]; h.y = acc[4 * q + 1]; h.z = acc[4 * q + 2]; h.w = acc[4 * q + 3]; *(f32x4*)(hrow + col + 4 * q) = h; }
	v_cvt_pk_f32_fp8_e32 v[120:121], v56
	v_cvt_pk_f32_fp8_sdwa v[122:123], v56 src0_sel:WORD_1
	v_cvt_pk_f32_fp8_e32 v[124:125], v57
	v_cvt_pk_f32_fp8_sdwa v[126:127], v57 src0_sel:WORD_1
	v_pk_fma_f32 v[156:157], v[120:121], v[152:153], v[156:157] op_sel_hi:[1,0,1]
	v_pk_fma_f32 v[158:159], v[122:123], v[152:153], v[158:159] op_sel_hi:[1,0,1]
	v_pk_fma_f32 v[160:161], v[124:125], v[152:153], v[160:161] op_sel_hi:[1,0,1]
	v_pk_fma_f32 v[162:163], v[126:127], v[152:153], v[162:163] op_sel_hi:[1,0,1]
	v_cvt_pk_f32_fp8_e32 v[120:121], v58
	v_cvt_pk_f32_fp8_sdwa v[122:123], v58 src0_sel:WORD_1
	v_cvt_pk_f32_fp8_e32 v[124:125], v59
	v_cvt_pk_f32_fp8_sdwa v[126:127], v59 src0_sel:WORD_1
	v_pk_fma_f32 v[166:167], v[120:121], v[152:153], v[166:167] op_sel_hi:[1,0,1]
	v_pk_fma_f32 v[168:169], v[122:123], v[152:153], v[168:169] op_sel_hi:[1,0,1]
	v_pk_fma_f32 v[170:171], v[124:125], v[152:153], v[170:171] op_sel_hi:[1,0,1]
	v_pk_fma_f32 v[172:173], v[126:127], v[152:153], v[172:173] op_sel_hi:[1,0,1]
	v_lshl_add_u32 v3, v84, 7, v0
	global_load_dwordx4 v[56:59], v3, s[40:41]
	s_waitcnt vmcnt(19)
	v_cvt_pk_f32_fp8_e32 v[120:121], v60
	v_cvt_pk_f32_fp8_sdwa v[122:123], v60 src0_sel:WORD_1
	v_cvt_pk_f32_fp8_e32 v[124:125], v61
	v_cvt_pk_f32_fp8_sdwa v[126:127], v61 src0_sel:WORD_1
	v_pk_fma_f32 v[156:157], v[120:121], v[152:153], v[156:157] op_sel:[0,1,0] op_sel_hi:[1,1,1]
	v_pk_fma_f32 v[158:159], v[122:123], v[152:153], v[158:159] op_sel:[0,1,0] op_sel_hi:[1,1,1]
	v_pk_fma_f32 v[160:161], v[124:125], v[152:153], v[160:161] op_sel:[0,1,0] op_sel_hi:[1,1,1]
	v_pk_fma_f32 v[162:163], v[126:127], v[152:153], v[162:163] op_sel:[0,1,0] op_sel_hi:[1,1,1]
	v_cvt_pk_f32_fp8_e32 v[120:121], v62
	v_cvt_pk_f32_fp8_sdwa v[122:123], v62 src0_sel:WORD_1
	v_cvt_pk_f32_fp8_e32 v[124:125], v63
	v_cvt_pk_f32_fp8_sdwa v[126:127], v63 src0_sel:WORD_1
	v_pk_fma_f32 v[166:167], v[120:121], v[152:153], v[166:167] op_sel:[0,1,0] op_sel_hi:[1,1,1]
	v_pk_fma_f32 v[168:169], v[122:123], v[152:153], v[168:169] op_sel:[0,1,0] op_sel_hi:[1,1,1]
	v_pk_fma_f32 v[170:171], v[124:125], v[152:153], v[170:171] op_sel:[0,1,0] op_sel_hi:[1,1,1]
	v_pk_fma_f32 v[172:173], v[126:127], v[152:153], v[172:173] op_sel:[0,1,0] op_sel_hi:[1,1,1]
	v_lshl_add_u32 v4, v85, 7, v0
	global_load_dwordx4 v[60:63], v4, s[40:41]
	s_waitcnt vmcnt(19)
	v_cvt_pk_f32_fp8_e32 v[120:121], v64
	v_cvt_pk_f32_fp8_sdwa v[122:123], v64 src0_sel:WORD_1
	v_cvt_pk_f32_fp8_e32 v[124:125], v65
	v_cvt_pk_f32_fp8_sdwa v[126:127], v65 src0_sel:WORD_1
	v_pk_fma_f32 v[156:157], v[120:121], v[154:155], v[156:157] op_sel_hi:[1,0,1]
	v_pk_fma_f32 v[158:159], v[122:123], v[154:155], v[158:159] op_sel_hi:[1,0,1]
	v_pk_fma_f32 v[160:161], v[124:125], v[154:155], v[160:161] op_sel_hi:[1,0,1]
	v_pk_fma_f32 v[162:163], v[126:127], v[154:155], v[162:163] op_sel_hi:[1,0,1]
	v_cvt_pk_f32_fp8_e32 v[120:121], v66
	v_cvt_pk_f32_fp8_sdwa v[122:123], v66 src0_sel:WORD_1
	v_cvt_pk_f32_fp8_e32 v[124:125], v67
	v_cvt_pk_f32_fp8_sdwa v[126:127], v67 src0_sel:WORD_1
	v_pk_fma_f32 v[166:167], v[120:121], v[154:155], v[166:167] op_sel_hi:[1,0,1]
	v_pk_fma_f32 v[168:169], v[122:123], v[154:155], v[168:169] op_sel_hi:[1,0,1]
	v_pk_fma_f32 v[170:171], v[124:125], v[154:155], v[170:171] op_sel_hi:[1,0,1]
	v_pk_fma_f32 v[172:173], v[126:127], v[154:155], v[172:173] op_sel_hi:[1,0,1]
	v_lshl_add_u32 v3, v86, 7, v0
	global_load_dwordx4 v[64:67], v3, s[40:41]
	s_waitcnt vmcnt(19)
	v_cvt_pk_f32_fp8_e32 v[120:121], v68
	v_cvt_pk_f32_fp8_sdwa v[122:123], v68 src0_sel:WORD_1
	v_cvt_pk_f32_fp8_e32 v[124:125], v69
	v_cvt_pk_f32_fp8_sdwa v[126:127], v69 src0_sel:WORD_1
	v_pk_fma_f32 v[156:157], v[120:121], v[154:155], v[156:157] op_sel:[0,1,0] op_sel_hi:[1,1,1]
	v_pk_fma_f32 v[158:159], v[122:123], v[154:155], v[158:159] op_sel:[0,1,0] op_sel_hi:[1,1,1]
	v_pk_fma_f32 v[160:161], v[124:125], v[154:155], v[160:161] op_sel:[0,1,0] op_sel_hi:[1,1,1]
	v_pk_fma_f32 v[162:163], v[126:127], v[154:155], v[162:163] op_sel:[0,1,0] op_sel_hi:[1,1,1]
	v_cvt_pk_f32_fp8_e32 v[120:121], v70
	v_cvt_pk_f32_fp8_sdwa v[122:123], v70 src0_sel:WORD_1
	v_cvt_pk_f32_fp8_e32 v[124:125], v71
	v_cvt_pk_f32_fp8_sdwa v[126:127], v71 src0_sel:WORD_1
	v_pk_fma_f32 v[166:167], v[120:121], v[154:155], v[166:167] op_sel:[0,1,0] op_sel_hi:[1,1,1]
	v_pk_fma_f32 v[168:169], v[122:123], v[154:155], v[168:169] op_sel:[0,1,0] op_sel_hi:[1,1,1]
	v_pk_fma_f32 v[170:171], v[124:125], v[154:155], v[170:171] op_sel:[0,1,0] op_sel_hi:[1,1,1]
	v_pk_fma_f32 v[172:173], v[126:127], v[154:155], v[172:173] op_sel:[0,1,0] op_sel_hi:[1,1,1]
	v_lshl_add_u32 v4, v87, 7, v0
	global_load_dwordx4 v[68:71], v4, s[40:41]
	s_waitcnt vmcnt(16)
	v_pk_add_f32 v[216:217], v[216:217], v[156:157]
	v_pk_add_f32 v[218:219], v[218:219], v[158:159]
	v_pk_add_f32 v[220:221], v[220:221], v[160:161]
	v_pk_add_f32 v[222:223], v[222:223], v[162:163]
	v_pk_add_f32 v[224:225], v[224:225], v[166:167]
	v_pk_add_f32 v[226:227], v[226:227], v[168:169]
	v_pk_add_f32 v[174:175], v[174:175], v[170:171]
	v_pk_add_f32 v[176:177], v[176:177], v[172:173]
	v_mov_b64_e32 v[156:157], 0
	v_mov_b64_e32 v[158:159], 0
	v_mov_b64_e32 v[160:161], 0
	v_mov_b64_e32 v[162:163], 0
	v_mov_b64_e32 v[166:167], 0
	v_mov_b64_e32 v[168:169], 0
	v_mov_b64_e32 v[170:171], 0
	v_mov_b64_e32 v[172:173], 0
	global_store_dwordx4 v2, v[216:219], s[42:43]
	global_store_dwordx4 v2, v[220:223], s[42:43] offset:16
	global_store_dwordx4 v2, v[224:227], s[42:43] offset:32
	global_store_dwordx4 v2, v[174:177], s[42:43] offset:48
